# rmsnorm: next row prefetched while the current row is normalised
# speedup vs baseline: 1.0167x; 1.0004x over previous
; __device__ __forceinline__ unsigned cvt_pk_bf16(float lo, float hi) { unsigned r; asm volatile("s_nop 0\n\tv_cvt_pk_bf16_f32 %0, %1, %2" : "=v"(r) : "v"(lo), "v"(hi)); return r; }
; __device__ __forceinline__ int fresh_tid() { int t = threadIdx.x; asm volatile("" : "+v"(t)); return t; }
; __device__ __forceinline__ void phase_norm(const float* x, const float* g, bf16_t* h) {
;     const int tid = fresh_tid(), wave = tid >> 6, lane = tid & 63;
;     for (int row = blockIdx.x * 8 + wave; row < SEQ; row += gridDim.x * 8) {
;         const f32x4* xr = (const f32x4*)(x + (size_t)row * DM) + lane;
;         f32x4 v[8]; float ss = 0.f;
; #pragma unroll
;         for (int j = 0; j < 8; ++j) { v[j] = xr[64 * j]; ss += v[j][0] * v[j][0] + v[j][1] * v[j][1] + v[j][2] * v[j][2] + v[j][3] * v[j][3]; }
;         const float rstd = rsqrtf(wave_sum(ss) * (1.f / DM) + EPS);
;         u32x2* o = (u32x2*)(h + (size_t)row * DM) + lane;
; #pragma unroll
;         for (int j = 0; j < 8; ++j) { const f32x4 gg = *((const f32x4*)g + lane + 64 * j);
;             u32x2 w; w.x = cvt_pk_bf16(v[j][0] * rstd * gg[0], v[j][1] * rstd * gg[1]); w.y = cvt_pk_bf16(v[j][2] * rstd * gg[2], v[j][3] * rstd * gg[3]); o[64 * j] = w; }
.LBB0_351:
	s_mov_b32 s6, s0
	v_writelane_b32 v255, s6, 46
	s_cmp_eq_u32 s0, 0
	s_cselect_b64 s[0:1], -1, 0
	v_writelane_b32 v255, s7, 47
	v_writelane_b32 v255, s0, 48
	s_mov_b64 s[6:7], s[94:95]
	v_mov_b32_e32 v0, v250
	v_writelane_b32 v255, s1, 49
	v_readlane_b32 s0, v253, 2
	v_ashrrev_i32_e32 v2, 6, v0
	v_readlane_b32 s1, v253, 3
	v_add_u32_e32 v6, s0, v2
	s_movk_i32 s0, 0x2000
	v_cmp_gt_i32_e32 vcc, s0, v6
	s_and_saveexec_b64 s[0:1], vcc
	s_cbranch_execz .LBB0_354
	v_cmp_lt_i32_e32 vcc, v245, v187
	v_readlane_b32 s20, v255, 48
	v_readlane_b32 s21, v255, 49
	v_cndmask_b32_e32 v3, v185, v245, vcc
	v_cmp_lt_i32_e32 vcc, v204, v187
	v_lshlrev_b32_e32 v22, 2, v3
	s_and_b64 s[20:21], s[20:21], exec
	v_cndmask_b32_e32 v3, v185, v204, vcc
	v_cmp_lt_i32_e32 vcc, v181, v187
	v_lshlrev_b32_e32 v23, 2, v3
	s_cselect_b32 s20, 0, 0xe8
	v_cndmask_b32_e32 v3, v185, v181, vcc
	v_cmp_lt_i32_e32 vcc, v252, v187
	v_lshlrev_b32_e32 v24, 2, v3
	s_add_u32 s20, s6, s20
	v_cndmask_b32_e32 v3, v185, v252, vcc
	v_lshlrev_b32_e32 v25, 2, v3
	v_xor_b32_e32 v3, 16, v185
	s_addc_u32 s21, s7, 0
	v_cmp_lt_i32_e32 vcc, v3, v187
	s_load_dwordx2 s[24:25], s[6:7], 0x10
	s_nop 0
	s_load_dwordx2 s[20:21], s[20:21], 0x0
	s_nop 0
	s_load_dwordx2 s[6:7], s[6:7], 0xf0
	v_cndmask_b32_e32 v3, v185, v3, vcc
	v_readlane_b32 s30, v255, 46
	v_lshlrev_b32_e32 v26, 2, v3
	v_xor_b32_e32 v3, 32, v185
	v_readlane_b32 s31, v255, 47
	s_lshl_b32 s38, s30, 11
	v_cmp_lt_i32_e32 vcc, v3, v187
	s_lshl_b64 s[30:31], s[38:39], 2
	v_and_b32_e32 v2, 63, v0
	v_cndmask_b32_e32 v3, v185, v3, vcc
	s_waitcnt lgkmcnt(0)
	s_add_u32 s24, s24, s30
	v_lshlrev_b32_e32 v0, 4, v2
	v_lshlrev_b32_e32 v27, 2, v3
	v_lshlrev_b32_e32 v2, 3, v2
	v_mov_b32_e32 v3, v1
	s_addc_u32 s25, s25, s31
	v_lshl_add_u64 v[2:3], s[6:7], 0, v[2:3]
	s_mov_b64 s[6:7], 0x15b00000
	v_lshl_add_u64 v[10:11], v[2:3], 0, s[6:7]
	v_lshl_add_u64 v[12:13], s[24:25], 0, v[0:1]
	s_mov_b64 s[6:7], 0x1400
	v_lshl_add_u64 v[16:17], v[12:13], 0, s[6:7]
	s_mov_b64 s[6:7], 0x1800
	v_lshl_add_u64 v[18:19], v[12:13], 0, s[6:7]
	s_mov_b64 s[6:7], 0x1c00
	v_lshl_add_u64 v[8:9], s[20:21], 0, v[0:1]
	v_lshl_add_u64 v[14:15], v[12:13], 0, s[14:15]
	v_lshl_add_u64 v[20:21], v[12:13], 0, s[6:7]
	s_mov_b64 s[6:7], 0
	global_load_dwordx4 v[104:107], v[12:13], off offset:1024
	global_load_dwordx4 v[108:111], v[12:13], off offset:2048
	global_load_dwordx4 v[112:115], v[12:13], off offset:3072
	global_load_dwordx4 v[116:119], v[14:15], off
	global_load_dwordx4 v[120:123], v[16:17], off
	global_load_dwordx4 v[124:127], v[18:19], off
	global_load_dwordx4 v[128:131], v[20:21], off
	v_ashrrev_i32_e32 v7, 31, v6
	v_lshlrev_b64 v[164:165], 13, v[6:7]
	v_lshl_add_u64 v[164:165], v[8:9], 0, v[164:165]
	global_load_dwordx4 v[132:135], v[164:165], off
	global_load_dwordx4 v[136:139], v[164:165], off offset:1024
	global_load_dwordx4 v[140:143], v[164:165], off offset:2048
	global_load_dwordx4 v[144:147], v[164:165], off offset:3072
	v_add_co_u32_e32 v164, vcc, s28, v164
	s_nop 1
	v_addc_co_u32_e32 v165, vcc, 0, v165, vcc
	global_load_dwordx4 v[148:151], v[164:165], off
	global_load_dwordx4 v[152:155], v[164:165], off offset:1024
	global_load_dwordx4 v[156:159], v[164:165], off offset:2048
	global_load_dwordx4 v[160:163], v[164:165], off offset:3072
	global_load_dwordx4 v[168:171], v[12:13], off
	s_waitcnt vmcnt(0)
.LBB0_353:
	s_waitcnt vmcnt(8)
	v_mov_b32_e32 v28, v132
	v_mov_b32_e32 v29, v133
	v_mov_b32_e32 v30, v134
	v_mov_b32_e32 v31, v135
	v_mov_b32_e32 v32, v136
	v_mov_b32_e32 v33, v137
	v_mov_b32_e32 v34, v138
	v_mov_b32_e32 v35, v139
	v_mov_b32_e32 v36, v140
	v_mov_b32_e32 v37, v141
	v_mov_b32_e32 v38, v142
	v_mov_b32_e32 v39, v143
	v_mov_b32_e32 v40, v144
	v_mov_b32_e32 v41, v145
	v_mov_b32_e32 v42, v146
	v_mov_b32_e32 v43, v147
	v_mov_b32_e32 v44, v148
	v_mov_b32_e32 v45, v149
	v_mov_b32_e32 v46, v150
	v_mov_b32_e32 v47, v151
	v_mov_b32_e32 v48, v152
	v_mov_b32_e32 v49, v153
	v_mov_b32_e32 v50, v154
	v_mov_b32_e32 v51, v155
	v_mov_b32_e32 v52, v156
	v_mov_b32_e32 v53, v157
	v_mov_b32_e32 v54, v158
	v_mov_b32_e32 v55, v159
	v_mov_b32_e32 v2, v160
	v_mov_b32_e32 v3, v161
	v_mov_b32_e32 v4, v162
	v_mov_b32_e32 v5, v163
	v_mov_b32_e32 v56, v168
	v_mov_b32_e32 v57, v169
	v_mov_b32_e32 v58, v170
	v_mov_b32_e32 v59, v171
	v_add_u32_e32 v164, s60, v6
	v_cmp_ge_i32_e32 vcc, s50, v164
	s_and_saveexec_b64 s[20:21], vcc
	s_cbranch_execz .Lmy_p1_nopf
	v_ashrrev_i32_e32 v165, 31, v164
	v_lshlrev_b64 v[164:165], 13, v[164:165]
	v_lshl_add_u64 v[164:165], v[8:9], 0, v[164:165]
	global_load_dwordx4 v[132:135], v[164:165], off
	global_load_dwordx4 v[136:139], v[164:165], off offset:1024
	global_load_dwordx4 v[140:143], v[164:165], off offset:2048
	global_load_dwordx4 v[144:147], v[164:165], off offset:3072
	v_add_co_u32_e32 v164, vcc, s28, v164
	s_nop 1
	v_addc_co_u32_e32 v165, vcc, 0, v165, vcc
	global_load_dwordx4 v[148:151], v[164:165], off
	global_load_dwordx4 v[152:155], v[164:165], off offset:1024
	global_load_dwordx4 v[156:159], v[164:165], off offset:2048
	global_load_dwordx4 v[160:163], v[164:165], off offset:3072
; __device__ __forceinline__ unsigned cvt_pk_bf16(float lo, float hi) { unsigned r; asm volatile("s_nop 0\n\tv_cvt_pk_bf16_f32 %0, %1, %2" : "=v"(r) : "v"(lo), "v"(hi)); return r; }
; __device__ __forceinline__ void phase_norm(const float* x, const float* g, bf16_t* h) {
;     ...
;         const f32x4* xr = (const f32x4*)(x + (size_t)row * DM) + lane;
;         f32x4 v[8]; float ss = 0.f;
; #pragma unroll
;         for (int j = 0; j < 8; ++j) { v[j] = xr[64 * j]; ss += v[j][0] * v[j][0] + v[j][1] * v[j][1] + v[j][2] * v[j][2] + v[j][3] * v[j][3]; }
;         const float rstd = rsqrtf(wave_sum(ss) * (1.f / DM) + EPS);
;         u32x2* o = (u32x2*)(h + (size_t)row * DM) + lane;
; #pragma unroll
;         for (int j = 0; j < 8; ++j) { const f32x4 gg = *((const f32x4*)g + lane + 64 * j);
;             u32x2 w; w.x = cvt_pk_bf16(v[j][0] * rstd * gg[0], v[j][1] * rstd * gg[1]); w.y = cvt_pk_bf16(v[j][2] * rstd * gg[2], v[j][3] * rstd * gg[3]); o[64 * j] = w; }
.Lmy_p1_nopf:
	s_or_b64 exec, exec, s[20:21]
	v_ashrrev_i32_e32 v7, 31, v6
	v_mul_f32_e32 v0, v29, v29
	v_mul_f32_e32 v76, v33, v33
	v_mul_f32_e32 v77, v37, v37
	v_fmac_f32_e32 v0, v28, v28
	v_fmac_f32_e32 v76, v32, v32
	v_mul_f32_e32 v78, v41, v41
	v_fmac_f32_e32 v77, v36, v36
	v_fmac_f32_e32 v0, v30, v30
	v_fmac_f32_e32 v76, v34, v34
	v_fmac_f32_e32 v78, v40, v40
	v_fmac_f32_e32 v77, v38, v38
	v_fmac_f32_e32 v0, v31, v31
	v_fmac_f32_e32 v76, v35, v35
	v_fmac_f32_e32 v78, v42, v42
	v_fmac_f32_e32 v77, v39, v39
	v_add_f32_e32 v0, v0, v76
	v_fmac_f32_e32 v78, v43, v43
	v_add_f32_e32 v0, v0, v77
	v_add_f32_e32 v0, v0, v78
	v_mov_b32_e32 v62, v45
	v_mov_b32_e32 v63, v49
	v_mov_b32_e32 v60, v44
	v_mov_b32_e32 v61, v48
	v_pk_mul_f32 v[62:63], v[62:63], v[62:63]
	v_mov_b32_e32 v64, v46
	v_mov_b32_e32 v65, v50
	v_mov_b32_e32 v70, v53
	v_mov_b32_e32 v71, v3
	v_pk_fma_f32 v[60:61], v[60:61], v[60:61], v[62:63]
	v_mov_b32_e32 v66, v47
	v_mov_b32_e32 v67, v51
	v_mov_b32_e32 v68, v52
	v_mov_b32_e32 v69, v2
	v_pk_mul_f32 v[70:71], v[70:71], v[70:71]
	v_pk_fma_f32 v[60:61], v[64:65], v[64:65], v[60:61]
	v_mov_b32_e32 v72, v54
	v_mov_b32_e32 v73, v4
	v_pk_fma_f32 v[62:63], v[68:69], v[68:69], v[70:71]
	v_pk_fma_f32 v[60:61], v[66:67], v[66:67], v[60:61]
	v_mov_b32_e32 v74, v55
	v_mov_b32_e32 v75, v5
	v_pk_fma_f32 v[62:63], v[72:73], v[72:73], v[62:63]
	v_add_f32_e32 v0, v0, v60
	v_pk_fma_f32 v[62:63], v[74:75], v[74:75], v[62:63]
	v_add_f32_e32 v0, v0, v61
	v_add_f32_e32 v0, v0, v62
	v_add_f32_e32 v0, v0, v63
	ds_bpermute_b32 v60, v22, v0
	s_waitcnt lgkmcnt(0)
	v_add_f32_e32 v0, v0, v60
	ds_bpermute_b32 v60, v23, v0
	s_waitcnt lgkmcnt(0)
	v_add_f32_e32 v0, v0, v60
	ds_bpermute_b32 v60, v24, v0
	s_waitcnt lgkmcnt(0)
	v_add_f32_e32 v0, v0, v60
	ds_bpermute_b32 v60, v25, v0
	s_waitcnt lgkmcnt(0)
	v_add_f32_e32 v0, v0, v60
	ds_bpermute_b32 v60, v26, v0
	s_waitcnt lgkmcnt(0)
	v_add_f32_e32 v0, v0, v60
	ds_bpermute_b32 v60, v27, v0
	s_waitcnt lgkmcnt(0)
	v_add_f32_e32 v0, v0, v60
	v_fmamk_f32 v0, v0, 0x3a000000, v242
	v_mul_f32_e32 v60, 0x4b800000, v0
	v_cmp_gt_f32_e32 vcc, s29, v0
	s_nop 1
	v_cndmask_b32_e32 v0, v0, v60, vcc
	v_rsq_f32_e32 v0, v0
	v_lshlrev_b64 v[60:61], 12, v[6:7]
	v_lshl_add_u64 v[60:61], v[10:11], 0, v[60:61]
	v_add_u32_e32 v6, s60, v6
	v_mul_f32_e32 v7, 0x45800000, v0
	v_cndmask_b32_e32 v0, v0, v7, vcc
	v_mul_f32_e32 v7, v28, v0
	v_mul_f32_e32 v28, v29, v0
	v_mul_f32_e32 v29, v30, v0
	v_mul_f32_e32 v30, v31, v0
	v_mul_f32_e32 v28, v57, v28
	v_mul_f32_e32 v29, v58, v29
	v_mul_f32_e32 v7, v56, v7
	v_mul_f32_e32 v30, v59, v30
	s_nop 0
	v_cvt_pk_bf16_f32 v28, v7, v28
	s_nop 0
	v_cvt_pk_bf16_f32 v29, v29, v30
	global_store_dwordx2 v[60:61], v[28:29], off
	v_mul_f32_e32 v7, v32, v0
	v_mul_f32_e32 v32, v33, v0
	v_mul_f32_e32 v33, v34, v0
	v_mul_f32_e32 v34, v35, v0
	v_cmp_lt_i32_e32 vcc, s50, v6
	v_mul_f32_e32 v2, v2, v0
	v_mul_f32_e32 v3, v3, v0
	v_mul_f32_e32 v4, v4, v0
	s_or_b64 s[6:7], vcc, s[6:7]
	v_mov_b32_e32 v28, v104
	v_mov_b32_e32 v29, v105
	v_mov_b32_e32 v30, v106
	v_mov_b32_e32 v31, v107
	v_mul_f32_e32 v7, v28, v7
	v_mul_f32_e32 v28, v29, v32
	v_mul_f32_e32 v29, v30, v33
	v_mul_f32_e32 v30, v31, v34
	s_nop 0
	v_cvt_pk_bf16_f32 v28, v7, v28
	s_nop 0
	v_cvt_pk_bf16_f32 v29, v29, v30
	global_store_dwordx2 v[60:61], v[28:29], off offset:512
	v_mul_f32_e32 v7, v36, v0
	v_mul_f32_e32 v32, v37, v0
	v_mul_f32_e32 v33, v38, v0
	v_mul_f32_e32 v34, v39, v0
	v_mov_b32_e32 v28, v108
	v_mov_b32_e32 v29, v109
	v_mov_b32_e32 v30, v110
	v_mov_b32_e32 v31, v111
	v_mul_f32_e32 v7, v28, v7
	v_mul_f32_e32 v28, v29, v32
	v_mul_f32_e32 v29, v30, v33
	v_mul_f32_e32 v30, v31, v34
	s_nop 0
	v_cvt_pk_bf16_f32 v28, v7, v28
	s_nop 0
	v_cvt_pk_bf16_f32 v29, v29, v30
	global_store_dwordx2 v[60:61], v[28:29], off offset:1024
	v_mul_f32_e32 v7, v40, v0
	v_mul_f32_e32 v32, v41, v0
	v_mul_f32_e32 v33, v42, v0
	v_mul_f32_e32 v34, v43, v0
	v_mov_b32_e32 v28, v112
	v_mov_b32_e32 v29, v113
	v_mov_b32_e32 v30, v114
	v_mov_b32_e32 v31, v115
	v_mul_f32_e32 v7, v7, v28
	v_mul_f32_e32 v28, v32, v29
	v_mul_f32_e32 v29, v33, v30
	v_mul_f32_e32 v30, v34, v31
	s_nop 0
	v_cvt_pk_bf16_f32 v28, v7, v28
	s_nop 0
	v_cvt_pk_bf16_f32 v29, v29, v30
	global_store_dwordx2 v[60:61], v[28:29], off offset:1536
	v_mul_f32_e32 v7, v44, v0
	v_mul_f32_e32 v32, v45, v0
	v_mul_f32_e32 v33, v46, v0
	v_mul_f32_e32 v34, v47, v0
	v_mov_b32_e32 v28, v116
	v_mov_b32_e32 v29, v117
	v_mov_b32_e32 v30, v118
	v_mov_b32_e32 v31, v119
	v_mul_f32_e32 v7, v7, v28
	v_mul_f32_e32 v28, v32, v29
	v_mul_f32_e32 v29, v33, v30
	v_mul_f32_e32 v30, v34, v31
	s_nop 0
	v_cvt_pk_bf16_f32 v28, v7, v28
	s_nop 0
	v_cvt_pk_bf16_f32 v29, v29, v30
	global_store_dwordx2 v[60:61], v[28:29], off offset:2048
	v_mul_f32_e32 v7, v48, v0
	v_mul_f32_e32 v32, v49, v0
	v_mul_f32_e32 v33, v50, v0
	v_mul_f32_e32 v34, v51, v0
	v_mov_b32_e32 v28, v120
	v_mov_b32_e32 v29, v121
	v_mov_b32_e32 v30, v122
	v_mov_b32_e32 v31, v123
	v_mul_f32_e32 v7, v7, v28
	v_mul_f32_e32 v28, v32, v29
	v_mul_f32_e32 v29, v33, v30
	v_mul_f32_e32 v30, v34, v31
	s_nop 0
	v_cvt_pk_bf16_f32 v28, v7, v28
	s_nop 0
	v_cvt_pk_bf16_f32 v29, v29, v30
	global_store_dwordx2 v[60:61], v[28:29], off offset:2560
	v_mul_f32_e32 v7, v52, v0
	v_mul_f32_e32 v32, v53, v0
	v_mul_f32_e32 v33, v54, v0
	v_mul_f32_e32 v34, v55, v0
	v_mul_f32_e32 v0, v5, v0
	v_mov_b32_e32 v28, v124
	v_mov_b32_e32 v29, v125
	v_mov_b32_e32 v30, v126
	v_mov_b32_e32 v31, v127
	v_mul_f32_e32 v7, v7, v28
	v_mul_f32_e32 v28, v32, v29
	v_mul_f32_e32 v29, v33, v30
	v_mul_f32_e32 v30, v34, v31
	s_nop 0
	v_cvt_pk_bf16_f32 v28, v7, v28
	s_nop 0
	v_cvt_pk_bf16_f32 v29, v29, v30
	global_store_dwordx2 v[60:61], v[28:29], off offset:3072
	v_mov_b32_e32 v28, v128
	v_mov_b32_e32 v29, v129
	v_mov_b32_e32 v30, v130
	v_mov_b32_e32 v31, v131
	v_mul_f32_e32 v2, v2, v28
	v_mul_f32_e32 v3, v3, v29
	v_mul_f32_e32 v4, v4, v30
	v_mul_f32_e32 v0, v0, v31
	s_nop 0
	v_cvt_pk_bf16_f32 v2, v2, v3
	s_nop 0
	v_cvt_pk_bf16_f32 v3, v4, v0
	global_store_dwordx2 v[60:61], v[2:3], off offset:3584
	s_andn2_b64 exec, exec, s[6:7]
	s_cbranch_execnz .LBB0_353
